# y phase: the masked (zero entering state) direction of two-chunk sequences loads the same lines as the other direction, no extra memory traffic
# baseline (speedup 1.0000x reference)
.LBB0_2101:
	s_ashr_i32 s12, s13, 3
	s_lshl_b32 s14, s12, 7
	v_add_u32_e32 v0, s14, v170
	v_ashrrev_i32_e32 v1, 31, v0
	v_readlane_b32 s16, v252, 47
	v_writelane_b32 v255, s13, 49
	s_and_b32 s13, s13, 7
	v_lshlrev_b64 v[0:1], 11, v[0:1]
	v_readlane_b32 s17, v252, 48
	v_readlane_b32 s22, v252, 12
	v_readlane_b32 s23, v252, 13
	v_lshl_add_u64 v[0:1], s[16:17], 0, v[0:1]
	s_lshl_b32 s22, s13, 8
	v_lshl_add_u64 v[0:1], v[0:1], 0, s[22:23]
	v_lshlrev_b32_e32 v2, 1, v172
	v_mov_b32_e32 v3, v129
	v_lshl_add_u64 v[0:1], v[0:1], 0, v[2:3]
	global_load_dwordx4 v[130:133], v[0:1], off
	global_load_dwordx4 v[134:137], v[0:1], off offset:32
	global_load_dwordx4 v[138:141], v[0:1], off offset:64
	global_load_dwordx4 v[142:145], v[0:1], off offset:96
	global_load_dwordx4 v[146:149], v[0:1], off offset:128
	global_load_dwordx4 v[150:153], v[0:1], off offset:160
	global_load_dwordx4 v[154:157], v[0:1], off offset:192
	global_load_dwordx4 v[158:161], v[0:1], off offset:224
	v_or_b32_e32 v0, s14, v173
	v_ashrrev_i32_e32 v1, 31, v0
	v_readlane_b32 s16, v252, 45
	v_lshlrev_b64 v[0:1], 11, v[0:1]
	v_readlane_b32 s17, v252, 46
	s_mov_b32 s15, 0x10000
	s_lshl_b32 s13, s13, 2
	v_lshl_add_u64 v[0:1], s[16:17], 0, v[0:1]
	v_lshl_add_u64 v[0:1], v[0:1], 0, s[22:23]
	v_lshl_add_u64 v[64:65], v[0:1], 0, v[2:3]
	v_add_co_u32_e32 v66, vcc, s15, v64
	s_mov_b32 s15, 0x20000
	s_nop 0
	v_addc_co_u32_e32 v67, vcc, 0, v65, vcc
	v_add_co_u32_e32 v68, vcc, s15, v64
	s_mov_b32 s15, 0x30000
	s_nop 0
	v_addc_co_u32_e32 v69, vcc, 0, v65, vcc
	v_add_co_u32_e32 v70, vcc, s15, v64
	v_writelane_b32 v255, s13, 50
	s_nop 0
	v_addc_co_u32_e32 v71, vcc, 0, v65, vcc
	s_ashr_i32 s13, s12, 31
	s_lshl_b64 s[20:21], s[12:13], 19
	v_readlane_b32 s16, v252, 43
	s_add_u32 s15, s16, s20
	v_writelane_b32 v255, s15, 51
	v_readlane_b32 s17, v252, 44
	v_writelane_b32 v255, s20, 52
	s_addc_u32 s15, s17, s21
	s_lshl_b64 s[16:17], s[12:13], 20
	v_writelane_b32 v255, s21, 53
	v_readlane_b32 s20, v252, 49
	v_writelane_b32 v255, s15, 54
	v_readlane_b32 s21, v252, 50
	s_add_u32 s15, s20, s16
	v_writelane_b32 v255, s15, 55
	s_addc_u32 s15, s21, s17
	v_writelane_b32 v255, s15, 56
	s_cmp_lt_u32 s12, 64
	s_cselect_b32 s15, 1, 0
	s_and_b32 s16, s12, 1
	s_xor_b32 s17, s16, 1
	s_and_b32 s17, s17, s15
	s_and_b32 s16, s16, s15
	s_add_i32 s20, s17, -1
	v_writelane_b32 v255, s20, 58
	s_add_i32 s20, s16, -1
	v_writelane_b32 v255, s20, 59
	s_xor_b32 s20, s16, 1
	s_lshl_b32 s20, s20, 19
	v_writelane_b32 v255, s20, 60
	s_lshl_b32 s17, s17, 19
	s_xor_b32 s20, s12, s15
	s_mov_b32 s21, 0
	s_lshl_b64 s[20:21], s[20:21], 19
	v_writelane_b32 v255, s20, 52
	v_writelane_b32 v255, s21, 53
	s_lshl_b64 s[20:21], s[20:21], 1
	s_add_u32 s20, s20, s17
	s_addc_u32 s21, s21, 0
	v_readlane_b32 s16, v252, 49
	v_readlane_b32 s17, v252, 50
	s_add_u32 s20, s20, s16
	s_addc_u32 s21, s21, s17
	v_writelane_b32 v255, s20, 55
	v_writelane_b32 v255, s21, 56
	s_mov_b32 s19, 0
	s_lshl_b64 s[12:13], s[12:13], 13
	global_load_dwordx4 v[76:79], v[64:65], off
	global_load_dwordx4 v[80:83], v[66:67], off
	global_load_dwordx4 v[84:87], v[68:69], off
	global_load_dwordx4 v[88:91], v[70:71], off
	global_load_dwordx4 v[92:95], v[64:65], off offset:32
	global_load_dwordx4 v[96:99], v[66:67], off offset:32
	global_load_dwordx4 v[100:103], v[68:69], off offset:32
	global_load_dwordx4 v[104:107], v[70:71], off offset:32
	global_load_dwordx4 v[108:111], v[64:65], off offset:64
	global_load_dwordx4 v[112:115], v[66:67], off offset:64
	global_load_dwordx4 v[116:119], v[68:69], off offset:64
	global_load_dwordx4 v[120:123], v[70:71], off offset:64
	global_load_dwordx4 v[124:127], v[64:65], off offset:96
	global_load_dwordx4 v[72:75], v[66:67], off offset:96
	global_load_dwordx4 v[212:215], v[68:69], off offset:96
	global_load_dwordx4 v[222:225], v[70:71], off offset:96
	global_load_dwordx4 v[234:237], v[64:65], off offset:128
	global_load_dwordx4 v[238:241], v[66:67], off offset:128
	global_load_dwordx4 v[242:245], v[68:69], off offset:128
	global_load_dwordx4 v[246:249], v[70:71], off offset:128
	s_waitcnt vmcnt(19)
	v_mfma_f32_32x32x16_bf16 v[0:15], v[76:79], v[130:133], 0
	global_load_dwordx4 v[76:79], v[64:65], off offset:160
	s_waitcnt vmcnt(19)
	v_mfma_f32_32x32x16_bf16 v[16:31], v[80:83], v[130:133], 0
	global_load_dwordx4 v[80:83], v[66:67], off offset:160
	s_waitcnt vmcnt(19)
	v_mfma_f32_32x32x16_bf16 v[32:47], v[84:87], v[130:133], 0
	global_load_dwordx4 v[84:87], v[68:69], off offset:160
	s_waitcnt vmcnt(19)
	v_mfma_f32_32x32x16_bf16 v[48:63], v[88:91], v[130:133], 0
	global_load_dwordx4 v[88:91], v[70:71], off offset:160
	s_waitcnt vmcnt(19)
	v_mfma_f32_32x32x16_bf16 v[0:15], v[92:95], v[134:137], v[0:15]
	global_load_dwordx4 v[92:95], v[64:65], off offset:192
	s_waitcnt vmcnt(19)
	v_mfma_f32_32x32x16_bf16 v[16:31], v[96:99], v[134:137], v[16:31]
	global_load_dwordx4 v[96:99], v[66:67], off offset:192
	s_waitcnt vmcnt(19)
	v_mfma_f32_32x32x16_bf16 v[32:47], v[100:103], v[134:137], v[32:47]
	global_load_dwordx4 v[100:103], v[68:69], off offset:192
	s_waitcnt vmcnt(19)
	v_mfma_f32_32x32x16_bf16 v[48:63], v[104:107], v[134:137], v[48:63]
	global_load_dwordx4 v[104:107], v[70:71], off offset:192
	s_waitcnt vmcnt(19)
	v_mfma_f32_32x32x16_bf16 v[0:15], v[108:111], v[138:141], v[0:15]
	global_load_dwordx4 v[108:111], v[64:65], off offset:224
	s_waitcnt vmcnt(19)
	v_mfma_f32_32x32x16_bf16 v[16:31], v[112:115], v[138:141], v[16:31]
	global_load_dwordx4 v[112:115], v[66:67], off offset:224
	s_waitcnt vmcnt(19)
	v_mfma_f32_32x32x16_bf16 v[32:47], v[116:119], v[138:141], v[32:47]
	global_load_dwordx4 v[116:119], v[68:69], off offset:224
	s_waitcnt vmcnt(19)
	v_mfma_f32_32x32x16_bf16 v[48:63], v[120:123], v[138:141], v[48:63]
	global_load_dwordx4 v[120:123], v[70:71], off offset:224
	s_waitcnt vmcnt(19)
	v_mfma_f32_32x32x16_bf16 v[0:15], v[124:127], v[142:145], v[0:15]
	s_waitcnt vmcnt(18)
	v_mfma_f32_32x32x16_bf16 v[16:31], v[72:75], v[142:145], v[16:31]
	s_waitcnt vmcnt(17)
	v_mfma_f32_32x32x16_bf16 v[32:47], v[212:215], v[142:145], v[32:47]
	s_waitcnt vmcnt(16)
	v_mfma_f32_32x32x16_bf16 v[48:63], v[222:225], v[142:145], v[48:63]
	s_waitcnt vmcnt(15)
	v_mfma_f32_32x32x16_bf16 v[0:15], v[234:237], v[146:149], v[0:15]
	s_waitcnt vmcnt(14)
	v_mfma_f32_32x32x16_bf16 v[16:31], v[238:241], v[146:149], v[16:31]
	s_waitcnt vmcnt(13)
	v_mfma_f32_32x32x16_bf16 v[32:47], v[242:245], v[146:149], v[32:47]
	s_waitcnt vmcnt(12)
	v_mfma_f32_32x32x16_bf16 v[48:63], v[246:249], v[146:149], v[48:63]
	s_waitcnt vmcnt(11)
	v_mfma_f32_32x32x16_bf16 v[0:15], v[76:79], v[150:153], v[0:15]
	s_waitcnt vmcnt(10)
	v_mfma_f32_32x32x16_bf16 v[16:31], v[80:83], v[150:153], v[16:31]
	s_waitcnt vmcnt(9)
	v_mfma_f32_32x32x16_bf16 v[32:47], v[84:87], v[150:153], v[32:47]
	s_waitcnt vmcnt(8)
	v_mfma_f32_32x32x16_bf16 v[48:63], v[88:91], v[150:153], v[48:63]
	s_waitcnt vmcnt(7)
	v_mfma_f32_32x32x16_bf16 v[0:15], v[92:95], v[154:157], v[0:15]
	s_waitcnt vmcnt(6)
	v_mfma_f32_32x32x16_bf16 v[16:31], v[96:99], v[154:157], v[16:31]
	s_waitcnt vmcnt(5)
	v_mfma_f32_32x32x16_bf16 v[32:47], v[100:103], v[154:157], v[32:47]
	s_waitcnt vmcnt(4)
	v_mfma_f32_32x32x16_bf16 v[48:63], v[104:107], v[154:157], v[48:63]
	s_waitcnt vmcnt(3)
	v_mfma_f32_32x32x16_bf16 v[0:15], v[108:111], v[158:161], v[0:15]
	s_waitcnt vmcnt(2)
	v_mfma_f32_32x32x16_bf16 v[16:31], v[112:115], v[158:161], v[16:31]
	s_waitcnt vmcnt(1)
	v_mfma_f32_32x32x16_bf16 v[32:47], v[116:119], v[158:161], v[32:47]
	s_waitcnt vmcnt(0)
	v_mfma_f32_32x32x16_bf16 v[48:63], v[120:123], v[158:161], v[48:63]
	v_add_u32_e32 v64, s14, v200
	v_ashrrev_i32_e32 v65, 31, v64
	v_readlane_b32 s14, v252, 41
	v_lshlrev_b64 v[64:65], 12, v[64:65]
	v_readlane_b32 s15, v252, 42
	s_nop 1
	v_lshl_add_u64 v[184:185], s[14:15], 0, v[64:65]
	s_branch .LBB0_2103

.LBB0_2103:
	v_writelane_b32 v255, s19, 57
	s_nop 0
	v_readlane_b32 s14, v255, 50
	s_add_i32 s22, s19, s14
	s_lshl_b32 s14, s22, 14
	v_readlane_b32 s15, v255, 51
	s_add_u32 s14, s15, s14
	v_readlane_b32 s15, v255, 54
	s_addc_u32 s15, s15, 0
	s_lshl_b64 s[16:17], s[22:23], 14
	v_readlane_b32 s19, v255, 55
	s_add_u32 s16, s19, s16
	v_readlane_b32 s19, v255, 56
	s_addc_u32 s17, s19, s17
	s_lshl_b64 s[20:21], s[22:23], 13
	v_readlane_b32 vcc_lo, v255, 52
	v_readlane_b32 vcc_hi, v255, 53
	s_add_u32 s20, s20, vcc_lo
	s_addc_u32 s21, s21, vcc_hi
	s_lshl_b64 s[20:21], s[20:21], 1
	v_readlane_b32 s100, v255, 60
	s_or_b32 s19, s20, s100
	v_readlane_b32 vcc_lo, v252, 49
	v_readlane_b32 vcc_hi, v252, 50
	s_add_u32 s20, vcc_lo, s19
	v_lshl_add_u64 v[64:65], s[14:15], 0, v[176:177]
	s_addc_u32 s21, vcc_hi, s21
	s_lshl_b32 s100, s22, 7
	s_add_u32 s100, s100, s12
	s_lshl_b32 s100, s100, 2
	s_mov_b32 s101, 0
	v_lshl_add_u64 v[222:223], s[100:101], 0, v[216:217]
	v_readlane_b32 s100, v255, 58
	v_readlane_b32 s101, v255, 59
	global_load_dwordx2 v[224:225], v[222:223], off
	global_load_dwordx4 v[64:67], v[64:65], off
	v_lshl_add_u64 v[68:69], s[16:17], 0, v[176:177]
	global_load_dwordx4 v[68:71], v[68:69], off
	v_lshl_add_u64 v[72:73], s[20:21], 0, v[176:177]
	global_load_dwordx4 v[72:75], v[72:73], off
	v_lshl_add_u64 v[76:77], s[14:15], 0, v[178:179]
	global_load_dwordx4 v[76:79], v[76:77], off
	v_lshl_add_u64 v[80:81], s[16:17], 0, v[178:179]
	global_load_dwordx4 v[80:83], v[80:81], off
	v_lshl_add_u64 v[84:85], s[20:21], 0, v[178:179]
	global_load_dwordx4 v[84:87], v[84:85], off
	v_lshl_add_u64 v[88:89], s[14:15], 0, v[180:181]
	global_load_dwordx4 v[88:91], v[88:89], off
	v_lshl_add_u64 v[92:93], s[16:17], 0, v[180:181]
	global_load_dwordx4 v[92:95], v[92:93], off
	v_lshl_add_u64 v[96:97], s[20:21], 0, v[180:181]
	global_load_dwordx4 v[96:99], v[96:97], off
	v_lshl_add_u64 v[100:101], s[14:15], 0, v[182:183]
	global_load_dwordx4 v[100:103], v[100:101], off
	v_lshl_add_u64 v[104:105], s[16:17], 0, v[182:183]
	global_load_dwordx4 v[104:107], v[104:105], off
	v_lshl_add_u64 v[108:109], s[20:21], 0, v[182:183]
	global_load_dwordx4 v[108:111], v[108:109], off
	v_writelane_b32 v252, s22, 12
	s_lshl_b32 s19, s22, 7
	s_mov_b64 s[14:15], -1
	v_writelane_b32 v252, s23, 13
	s_mov_b32 s20, 0
	s_barrier
	s_waitcnt vmcnt(11)
	ds_write_b64 v226, v[224:225]
	ds_write_b128 v201, v[64:67]
	s_waitcnt vmcnt(10)
	v_and_b32_e32 v68, s100, v68
	v_and_b32_e32 v69, s100, v69
	v_and_b32_e32 v70, s100, v70
	v_and_b32_e32 v71, s100, v71
	ds_write_b128 v201, v[68:71] offset:17408
	s_waitcnt vmcnt(9)
	v_and_b32_e32 v72, s101, v72
	v_and_b32_e32 v73, s101, v73
	v_and_b32_e32 v74, s101, v74
	v_and_b32_e32 v75, s101, v75
	ds_write_b128 v201, v[72:75] offset:34816
	s_waitcnt vmcnt(8)
	ds_write_b128 v202, v[76:79]
	s_waitcnt vmcnt(7)
	v_and_b32_e32 v80, s100, v80
	v_and_b32_e32 v81, s100, v81
	v_and_b32_e32 v82, s100, v82
	v_and_b32_e32 v83, s100, v83
	ds_write_b128 v202, v[80:83] offset:17408
	s_waitcnt vmcnt(6)
	v_and_b32_e32 v84, s101, v84
	v_and_b32_e32 v85, s101, v85
	v_and_b32_e32 v86, s101, v86
	v_and_b32_e32 v87, s101, v87
	ds_write_b128 v202, v[84:87] offset:34816
	s_waitcnt vmcnt(5)
	ds_write_b128 v203, v[88:91]
	s_waitcnt vmcnt(4)
	v_and_b32_e32 v92, s100, v92
	v_and_b32_e32 v93, s100, v93
	v_and_b32_e32 v94, s100, v94
	v_and_b32_e32 v95, s100, v95
	ds_write_b128 v203, v[92:95] offset:17408
	s_waitcnt vmcnt(3)
	v_and_b32_e32 v96, s101, v96
	v_and_b32_e32 v97, s101, v97
	v_and_b32_e32 v98, s101, v98
	v_and_b32_e32 v99, s101, v99
	ds_write_b128 v203, v[96:99] offset:34816
	s_waitcnt vmcnt(2)
	ds_write_b128 v204, v[100:103]
	s_waitcnt vmcnt(1)
	v_and_b32_e32 v104, s100, v104
	v_and_b32_e32 v105, s100, v105
	v_and_b32_e32 v106, s100, v106
	v_and_b32_e32 v107, s100, v107
	ds_write_b128 v204, v[104:107] offset:17408
	s_waitcnt vmcnt(0)
	v_and_b32_e32 v108, s101, v108
	v_and_b32_e32 v109, s101, v109
	v_and_b32_e32 v110, s101, v110
	v_and_b32_e32 v111, s101, v111
	ds_write_b128 v204, v[108:111] offset:34816
	v_mov_b32_e32 v78, v129
	v_mov_b32_e32 v79, v129
	v_mov_b32_e32 v64, v129
	v_mov_b32_e32 v65, v129
	v_mov_b32_e32 v66, v129
	v_mov_b32_e32 v67, v129
	v_mov_b32_e32 v68, v129
	v_mov_b32_e32 v69, v129
	v_mov_b32_e32 v70, v129
	v_mov_b32_e32 v71, v129
	v_mov_b32_e32 v72, v129
	v_mov_b32_e32 v73, v129
	v_mov_b32_e32 v74, v129
	v_mov_b32_e32 v75, v129
	v_mov_b32_e32 v76, v129
	v_mov_b32_e32 v77, v129
	v_mov_b64_e32 v[94:95], v[78:79]
	v_mov_b64_e32 v[92:93], v[76:77]
	v_mov_b64_e32 v[90:91], v[74:75]
	v_mov_b64_e32 v[88:89], v[72:73]
	v_mov_b64_e32 v[86:87], v[70:71]
	v_mov_b64_e32 v[84:85], v[68:69]
	v_mov_b64_e32 v[82:83], v[66:67]
	v_mov_b64_e32 v[80:81], v[64:65]
	s_waitcnt lgkmcnt(0)
	s_barrier
	s_branch .LBB0_2105
